# K-loop heads (all three copies) aligned to 64 bytes (code placement)
# baseline (speedup 1.0000x reference)
; #define PG8_STAGE(bufoff, gbase, voff) do { _Pragma("unroll") for (int _i = 0; _i < 2; ++_i) \
;         __builtin_amdgcn_global_load_lds((const unsigned*)((const char*)(gbase) + (voff)[_i]), (PG8_LAS unsigned*)(lds + (bufoff) + ldsw + _i * 8192), 16, 0, 0); } while (0)
; #define PG8_LDA(dst, b, h) do { _Pragma("unroll") for (int m = 0; m < 4; ++m) _Pragma("unroll") for (int k = 0; k < 2; ++k) dst[m][k] = *(const PG8_LAS bf16x8*)(lds + PG8_SA(b, h) + aoff + m * 2048 + k * 1024); } while (0)
; #define PG8_LDB(dst, b, h) do { _Pragma("unroll") for (int n = 0; n < 2; ++n) _Pragma("unroll") for (int k = 0; k < 2; ++k) dst[n][k] = *(const PG8_LAS bf16x8*)(lds + PG8_SB(b, h) + boff + n * 2048 + k * 1024); } while (0)
; #define PG8_MMA(ai, bj, At, Bt) do { __builtin_amdgcn_s_setprio(1); _Pragma("unroll") for (int m = 0; m < 4; ++m) _Pragma("unroll") for (int n = 0; n < 2; ++n) _Pragma("unroll") for (int k = 0; k < 2; ++k) \
;         acc[ai][bj][m][n] = __builtin_amdgcn_mfma_f32_16x16x32_bf16(Bt[n][k], At[m][k], acc[ai][bj][m][n], 0, 0, 0); __builtin_amdgcn_s_setprio(0); } while (0)
; #define PG8_WAIT_V(n) asm volatile("s_waitcnt vmcnt(" #n ")" ::: "memory")
; template <class Epi, class Sched, bool ALIGN_EPI = false, bool SP2 = false>
; __device__ __forceinline__ void gemm_phase(PG8_LAS unsigned char* lds, const Gemm g, const Sched& S, const Epi& E, const int wave_s) {
;     ...
;         const bool has_next = S.next(ui + 1, nxt);
;         const char* nA = has_next ? (const char*)g.A + (size_t)nxt.pm * tstep + (size_t)nxt.k0 * kstep : cA; const char* nB = has_next ? (const char*)g.Bt + (size_t)nxt.pn * tstep + (size_t)nxt.k0 * kstep : cB;
;         const int clen = cur.len;
;         for (int t = 0; t < clen; t += 2) {
;             const bool last = (t == clen - 2);
;             const char* a1 = cA + (size_t)(t + 1) * kstep;
;             const char* a2 = last ? nA : cA + (size_t)(t + 2) * kstep; const char* b2 = last ? nB : cB + (size_t)(t + 2) * kstep;
;             const char* a3 = a2 + kstep; const char* b3 = b2 + kstep;
;             if (last && has_next) S.a_ready(nxt);
;             if constexpr (SP2) {
;             PG8_LDB(B0, 0, 0); PG8_LDB(B1, 0, 1); PG8_SCHED; PG8_LDA(At, 0, 0); PG8_STAGE(PG8_SA(1, 1), a1 + hstep, voffA);
;             PG8_WAIT_V(8); PG8_WAIT_L(0); PG8_BAR; PG8_MMA(0, 0, At, B0); PG8_MMA(0, 1, At, B1); PG8_BAR; PG8_SCHED;
.LBB0_300:
	s_ashr_i32 s25, s24, 31
	s_lshl_b64 s[26:27], s[24:25], 19
	s_add_u32 s26, s38, s26
	s_addc_u32 s27, s39, s27
	s_and_b64 s[28:29], s[6:7], exec
	s_cselect_b32 s9, s27, s35
	s_cselect_b32 s25, s26, s34
	s_ashr_i32 s23, s22, 31
	s_lshl_b64 s[28:29], s[22:23], 19
	s_add_u32 s28, s40, s28
	s_addc_u32 s29, s41, s29
	s_and_b64 s[36:37], s[6:7], exec
	s_cselect_b32 s23, s29, s3
	s_cselect_b32 s31, s28, s2
	s_add_u32 s34, s34, 0x40080
	s_addc_u32 s35, s35, 0
	s_add_u32 s52, s2, 0x100
	s_addc_u32 s53, s3, 0
	s_mov_b32 s54, -2
	s_add_u32 s2, s34, 0xfffc0080
	s_addc_u32 s3, s35, -1
	s_add_i32 s55, 0, 0x10000
	s_cmp_eq_u32 s54, 12
	s_cselect_b32 s37, s9, s3
	s_cselect_b32 s36, s25, s2
	s_cselect_b32 s3, s23, s53
	s_cselect_b32 s2, s31, s52
	s_add_i32 s58, 0, 0x14000
	v_add_u32_e32 v156, s55, v146
	v_add_u32_e32 v160, s58, v146
	ds_read_b128 v[140:143], v156
	ds_read_b128 v[148:151], v156 offset:1024
	ds_read_b128 v[152:155], v156 offset:2048
	ds_read_b128 v[156:159], v156 offset:3072
	ds_read_b128 v[174:177], v160
	ds_read_b128 v[178:181], v160 offset:1024
	ds_read_b128 v[182:185], v160 offset:2048
	ds_read_b128 v[186:189], v160 offset:3072
	v_lshl_add_u64 v[160:161], s[34:35], 0, v[136:137]
	s_add_i32 m0, s43, 0xc000
	ds_read_b128 v[190:193], v147
	ds_read_b128 v[210:213], v147 offset:1024
	ds_read_b128 v[214:217], v147 offset:2048
	ds_read_b128 v[218:221], v147 offset:3072
	ds_read_b128 v[222:225], v147 offset:4096
	ds_read_b128 v[226:229], v147 offset:5120
	ds_read_b128 v[230:233], v147 offset:6144
	ds_read_b128 v[234:237], v147 offset:7168
	global_load_lds_dwordx4 v[160:161], off
	v_lshl_add_u64 v[160:161], s[34:35], 0, v[138:139]
	s_add_i32 m0, s43, 0xe000
	s_nop 0
	global_load_lds_dwordx4 v[160:161], off
	s_waitcnt vmcnt(8)
	s_waitcnt lgkmcnt(0)
	s_barrier
	s_setprio 1
	s_waitcnt lgkmcnt(0)
	v_mfma_f32_16x16x32_bf16 v[124:127], v[140:143], v[190:193], 0
	v_mfma_f32_16x16x32_bf16 v[120:123], v[152:155], v[190:193], 0
	v_mfma_f32_16x16x32_bf16 v[108:111], v[140:143], v[214:217], 0
	v_mfma_f32_16x16x32_bf16 v[104:107], v[152:155], v[214:217], 0
	v_mfma_f32_16x16x32_bf16 v[92:95], v[140:143], v[222:225], 0
	v_mfma_f32_16x16x32_bf16 v[88:91], v[152:155], v[222:225], 0
	v_mfma_f32_16x16x32_bf16 v[76:79], v[140:143], v[230:233], 0
	v_mfma_f32_16x16x32_bf16 v[72:75], v[152:155], v[230:233], 0
	v_mfma_f32_16x16x32_bf16 v[124:127], v[148:151], v[210:213], v[124:127]
	v_mfma_f32_16x16x32_bf16 v[120:123], v[156:159], v[210:213], v[120:123]
	v_mfma_f32_16x16x32_bf16 v[108:111], v[148:151], v[218:221], v[108:111]
	v_mfma_f32_16x16x32_bf16 v[104:107], v[156:159], v[218:221], v[104:107]
	v_mfma_f32_16x16x32_bf16 v[92:95], v[148:151], v[226:229], v[92:95]
	v_mfma_f32_16x16x32_bf16 v[88:91], v[156:159], v[226:229], v[88:91]
	v_mfma_f32_16x16x32_bf16 v[76:79], v[148:151], v[234:237], v[76:79]
	v_mfma_f32_16x16x32_bf16 v[72:75], v[156:159], v[234:237], v[72:75]
	s_setprio 0
	s_setprio 1
	v_mfma_f32_16x16x32_bf16 v[116:119], v[174:177], v[190:193], 0
	v_mfma_f32_16x16x32_bf16 v[112:115], v[182:185], v[190:193], 0
	v_mfma_f32_16x16x32_bf16 v[100:103], v[174:177], v[214:217], 0
	v_mfma_f32_16x16x32_bf16 v[96:99], v[182:185], v[214:217], 0
	v_mfma_f32_16x16x32_bf16 v[84:87], v[174:177], v[222:225], 0
	v_mfma_f32_16x16x32_bf16 v[80:83], v[182:185], v[222:225], 0
	v_mfma_f32_16x16x32_bf16 v[68:71], v[174:177], v[230:233], 0
	v_mfma_f32_16x16x32_bf16 v[64:67], v[182:185], v[230:233], 0
	v_mfma_f32_16x16x32_bf16 v[116:119], v[178:181], v[210:213], v[116:119]
	v_mfma_f32_16x16x32_bf16 v[112:115], v[186:189], v[210:213], v[112:115]
	v_mfma_f32_16x16x32_bf16 v[100:103], v[178:181], v[218:221], v[100:103]
	v_mfma_f32_16x16x32_bf16 v[96:99], v[186:189], v[218:221], v[96:99]
	v_mfma_f32_16x16x32_bf16 v[84:87], v[178:181], v[226:229], v[84:87]
	v_mfma_f32_16x16x32_bf16 v[80:83], v[186:189], v[226:229], v[80:83]
	v_mfma_f32_16x16x32_bf16 v[68:71], v[178:181], v[234:237], v[68:71]
	v_mfma_f32_16x16x32_bf16 v[64:67], v[186:189], v[234:237], v[64:67]
	s_setprio 0
	s_barrier
; #define PG8_STAGE(bufoff, gbase, voff) do { _Pragma("unroll") for (int _i = 0; _i < 2; ++_i) \
;         __builtin_amdgcn_global_load_lds((const unsigned*)((const char*)(gbase) + (voff)[_i]), (PG8_LAS unsigned*)(lds + (bufoff) + ldsw + _i * 8192), 16, 0, 0); } while (0)
; #define PG8_LDA(dst, b, h) do { _Pragma("unroll") for (int m = 0; m < 4; ++m) _Pragma("unroll") for (int k = 0; k < 2; ++k) dst[m][k] = *(const PG8_LAS bf16x8*)(lds + PG8_SA(b, h) + aoff + m * 2048 + k * 1024); } while (0)
; #define PG8_MMA(ai, bj, At, Bt) do { __builtin_amdgcn_s_setprio(1); _Pragma("unroll") for (int m = 0; m < 4; ++m) _Pragma("unroll") for (int n = 0; n < 2; ++n) _Pragma("unroll") for (int k = 0; k < 2; ++k) \
;         acc[ai][bj][m][n] = __builtin_amdgcn_mfma_f32_16x16x32_bf16(Bt[n][k], At[m][k], acc[ai][bj][m][n], 0, 0, 0); __builtin_amdgcn_s_setprio(0); } while (0)
; #define PG8_WAIT_V(n) asm volatile("s_waitcnt vmcnt(" #n ")" ::: "memory")
; #define PG8_WAIT_L(n) asm volatile("s_waitcnt lgkmcnt(" #n ")" ::: "memory")
; #define PG8_BAR __builtin_amdgcn_s_barrier()
; #define PG8_SCHED __builtin_amdgcn_sched_barrier(0)
; template <class Epi, class Sched, bool ALIGN_EPI = false, bool SP2 = false>
; __device__ __forceinline__ void gemm_phase(PG8_LAS unsigned char* lds, const Gemm g, const Sched& S, const Epi& E, const int wave_s) {
;     ...
;             PG8_LDA(At, 0, 1); PG8_STAGE(PG8_SB(0, 0), b2, voffB); PG8_STAGE(PG8_SB(0, 1), b2 + hstep, voffB); PG8_STAGE(PG8_SA(0, 0), a2, voffA);
;             PG8_WAIT_V(8); PG8_WAIT_L(0); PG8_BAR; PG8_MMA(1, 0, At, B0); PG8_MMA(1, 1, At, B1); PG8_BAR; PG8_SCHED;
	s_add_i32 s55, s55, s42
	v_lshl_add_u64 v[160:161], s[2:3], 0, v[128:129]
	s_mov_b32 m0, s55
	ds_read_b128 v[190:193], v147 offset:16384
	ds_read_b128 v[210:213], v147 offset:17408
	ds_read_b128 v[214:217], v147 offset:18432
	ds_read_b128 v[218:221], v147 offset:19456
	ds_read_b128 v[222:225], v147 offset:20480
	ds_read_b128 v[226:229], v147 offset:21504
	ds_read_b128 v[230:233], v147 offset:22528
	ds_read_b128 v[234:237], v147 offset:23552
	global_load_lds_dwordx4 v[160:161], off
	s_add_i32 m0, s55, 0x2000
	s_add_u32 s56, s2, 0x40000
	v_lshl_add_u64 v[194:195], s[2:3], 0, v[134:135]
	s_addc_u32 s57, s3, 0
	s_add_i32 s55, s58, s42
	global_load_lds_dwordx4 v[194:195], off
	v_lshl_add_u64 v[206:207], s[56:57], 0, v[128:129]
	s_mov_b32 m0, s55
	v_lshl_add_u64 v[238:239], s[36:37], 0, v[132:133]
	global_load_lds_dwordx4 v[206:207], off
	v_lshl_add_u64 v[206:207], s[56:57], 0, v[134:135]
	s_add_i32 m0, s55, 0x2000
	s_nop 0
	global_load_lds_dwordx4 v[206:207], off
	v_lshl_add_u64 v[206:207], s[36:37], 0, v[130:131]
	s_mov_b32 m0, s43
	s_nop 0
	global_load_lds_dwordx4 v[206:207], off
	s_mov_b32 m0, s44
	s_nop 0
	global_load_lds_dwordx4 v[238:239], off
	s_waitcnt vmcnt(8)
	s_waitcnt lgkmcnt(0)
	s_barrier
	s_setprio 1
	s_waitcnt lgkmcnt(0)
	v_mfma_f32_16x16x32_bf16 v[60:63], v[140:143], v[190:193], 0
	v_mfma_f32_16x16x32_bf16 v[56:59], v[152:155], v[190:193], 0
	v_mfma_f32_16x16x32_bf16 v[44:47], v[140:143], v[214:217], 0
	v_mfma_f32_16x16x32_bf16 v[40:43], v[152:155], v[214:217], 0
	v_mfma_f32_16x16x32_bf16 v[28:31], v[140:143], v[222:225], 0
	v_mfma_f32_16x16x32_bf16 v[24:27], v[152:155], v[222:225], 0
	v_mfma_f32_16x16x32_bf16 v[12:15], v[140:143], v[230:233], 0
	v_mfma_f32_16x16x32_bf16 v[8:11], v[152:155], v[230:233], 0
	v_mfma_f32_16x16x32_bf16 v[60:63], v[148:151], v[210:213], v[60:63]
	v_mfma_f32_16x16x32_bf16 v[56:59], v[156:159], v[210:213], v[56:59]
	v_mfma_f32_16x16x32_bf16 v[44:47], v[148:151], v[218:221], v[44:47]
	v_mfma_f32_16x16x32_bf16 v[40:43], v[156:159], v[218:221], v[40:43]
	v_mfma_f32_16x16x32_bf16 v[28:31], v[148:151], v[226:229], v[28:31]
	v_mfma_f32_16x16x32_bf16 v[24:27], v[156:159], v[226:229], v[24:27]
	v_mfma_f32_16x16x32_bf16 v[12:15], v[148:151], v[234:237], v[12:15]
	v_mfma_f32_16x16x32_bf16 v[8:11], v[156:159], v[234:237], v[8:11]
	s_setprio 0
	s_setprio 1
	v_mfma_f32_16x16x32_bf16 v[52:55], v[174:177], v[190:193], 0
	v_mfma_f32_16x16x32_bf16 v[48:51], v[182:185], v[190:193], 0
	v_mfma_f32_16x16x32_bf16 v[36:39], v[174:177], v[214:217], 0
	v_mfma_f32_16x16x32_bf16 v[32:35], v[182:185], v[214:217], 0
	v_mfma_f32_16x16x32_bf16 v[20:23], v[174:177], v[222:225], 0
	v_mfma_f32_16x16x32_bf16 v[16:19], v[182:185], v[222:225], 0
	v_mfma_f32_16x16x32_bf16 v[4:7], v[174:177], v[230:233], 0
	v_mfma_f32_16x16x32_bf16 v[0:3], v[182:185], v[230:233], 0
	v_mfma_f32_16x16x32_bf16 v[52:55], v[178:181], v[210:213], v[52:55]
	v_mfma_f32_16x16x32_bf16 v[48:51], v[186:189], v[210:213], v[48:51]
	v_mfma_f32_16x16x32_bf16 v[36:39], v[178:181], v[218:221], v[36:39]
	v_mfma_f32_16x16x32_bf16 v[32:35], v[186:189], v[218:221], v[32:35]
	v_mfma_f32_16x16x32_bf16 v[20:23], v[178:181], v[226:229], v[20:23]
	v_mfma_f32_16x16x32_bf16 v[16:19], v[186:189], v[226:229], v[16:19]
	v_mfma_f32_16x16x32_bf16 v[4:7], v[178:181], v[234:237], v[4:7]
	v_mfma_f32_16x16x32_bf16 v[0:3], v[186:189], v[234:237], v[0:3]
	s_setprio 0
	s_barrier
	s_branch .Lpeel0_seg3
	.p2align	6

; template <class Epi, class Sched, bool ALIGN_EPI = false, bool SP2 = false>
; __device__ __forceinline__ void gemm_phase(PG8_LAS unsigned char* lds, const Gemm g, const Sched& S, const Epi& E, const int wave_s) {
;     ...
;         const int clen = cur.len;
;         for (int t = 0; t < clen; t += 2) {
;             const bool last = (t == clen - 2);
;             const char* a1 = cA + (size_t)(t + 1) * kstep;
;             const char* a2 = last ? nA : cA + (size_t)(t + 2) * kstep; const char* b2 = last ? nB : cB + (size_t)(t + 2) * kstep;
;             const char* a3 = a2 + kstep; const char* b3 = b2 + kstep;
.LBB0_368:
	s_xor_b64 s[2:3], s[2:3], -1
	s_add_i32 s17, s55, -2
	s_add_u32 s34, s34, 0x80
	s_addc_u32 s35, s35, 0
	s_add_u32 s57, s8, 0x100
	s_addc_u32 s58, s9, 0
	s_mov_b32 s8, 0
	.p2align	6

; #define PG8_STAGE(bufoff, gbase, voff) do { _Pragma("unroll") for (int _i = 0; _i < 2; ++_i) \
;         __builtin_amdgcn_global_load_lds((const unsigned*)((const char*)(gbase) + (voff)[_i]), (PG8_LAS unsigned*)(lds + (bufoff) + ldsw + _i * 8192), 16, 0, 0); } while (0)
; #define PG8_LDA(dst, b, h) do { _Pragma("unroll") for (int m = 0; m < 4; ++m) _Pragma("unroll") for (int k = 0; k < 2; ++k) dst[m][k] = *(const PG8_LAS bf16x8*)(lds + PG8_SA(b, h) + aoff + m * 2048 + k * 1024); } while (0)
; #define PG8_LDB(dst, b, h) do { _Pragma("unroll") for (int n = 0; n < 2; ++n) _Pragma("unroll") for (int k = 0; k < 2; ++k) dst[n][k] = *(const PG8_LAS bf16x8*)(lds + PG8_SB(b, h) + boff + n * 2048 + k * 1024); } while (0)
; #define PG8_WAIT_V(n) asm volatile("s_waitcnt vmcnt(" #n ")" ::: "memory")
; #define PG8_WAIT_L(n) asm volatile("s_waitcnt lgkmcnt(" #n ")" ::: "memory")
; template <class Epi, class Sched, bool ALIGN_EPI = false, bool SP2 = false>
; __device__ __forceinline__ void gemm_phase(PG8_LAS unsigned char* lds, const Gemm g, const Sched& S, const Epi& E, const int wave_s) {
;     ...
;         const bool has_next = S.next(ui + 1, nxt);
;         const char* nA = has_next ? (const char*)g.A + (size_t)nxt.pm * tstep + (size_t)nxt.k0 * kstep : cA; const char* nB = has_next ? (const char*)g.Bt + (size_t)nxt.pn * tstep + (size_t)nxt.k0 * kstep : cB;
;         const int clen = cur.len;
;         for (int t = 0; t < clen; t += 2) {
;             const bool last = (t == clen - 2);
;             const char* a1 = cA + (size_t)(t + 1) * kstep;
;             const char* a2 = last ? nA : cA + (size_t)(t + 2) * kstep; const char* b2 = last ? nB : cB + (size_t)(t + 2) * kstep;
;             const char* a3 = a2 + kstep; const char* b3 = b2 + kstep;
;             if (last && has_next) S.a_ready(nxt);
;             if constexpr (SP2) {
;             PG8_LDB(B0, 0, 0); PG8_LDB(B1, 0, 1); PG8_SCHED; PG8_LDA(At, 0, 0); PG8_STAGE(PG8_SA(1, 1), a1 + hstep, voffA);
;             PG8_WAIT_V(8); PG8_WAIT_L(0); PG8_BAR; PG8_MMA(0, 0, At, B0); PG8_MMA(0, 1, At, B1); PG8_BAR; PG8_SCHED;
;             PG8_LDA(At, 0, 1); PG8_STAGE(PG8_SB(0, 0), b2, voffB); PG8_STAGE(PG8_SB(0, 1), b2 + hstep, voffB); PG8_STAGE(PG8_SA(0, 0), a2, voffA);
;             PG8_WAIT_V(8); PG8_WAIT_L(0); PG8_BAR; PG8_MMA(1, 0, At, B0); PG8_MMA(1, 1, At, B1); PG8_BAR; PG8_SCHED;
.Lgum_522:
	s_ashr_i32 s19, s18, 31
	s_lshl_b64 s[20:21], s[18:19], 19
	s_add_u32 s20, s28, s20
	s_addc_u32 s21, s29, s21
	s_and_b64 s[22:23], s[6:7], exec
	s_cselect_b32 s19, s21, s25
	s_cselect_b32 s46, s20, s24
	s_ashr_i32 s17, s16, 31
	s_lshl_b64 s[22:23], s[16:17], 19
	s_add_u32 s22, s30, s22
	s_addc_u32 s23, s31, s23
	s_and_b64 s[100:101], s[6:7], exec
	s_cselect_b32 s17, s23, s49
	s_cselect_b32 s47, s22, s48
	s_waitcnt vmcnt(8)
	s_waitcnt lgkmcnt(0)
	s_barrier
	s_setprio 1
	s_waitcnt lgkmcnt(0)
	v_mfma_f32_16x16x32_bf16 v[124:127], v[140:143], v[190:193], 0
	v_mfma_f32_16x16x32_bf16 v[116:119], v[154:157], v[190:193], 0
	v_mfma_f32_16x16x32_bf16 v[108:111], v[140:143], v[214:217], 0
	v_mfma_f32_16x16x32_bf16 v[100:103], v[154:157], v[214:217], 0
	v_mfma_f32_16x16x32_bf16 v[92:95], v[140:143], v[222:225], 0
	v_mfma_f32_16x16x32_bf16 v[84:87], v[154:157], v[222:225], 0
	v_mfma_f32_16x16x32_bf16 v[76:79], v[140:143], v[230:233], 0
	v_mfma_f32_16x16x32_bf16 v[68:71], v[154:157], v[230:233], 0
	v_mfma_f32_16x16x32_bf16 v[124:127], v[150:153], v[210:213], v[124:127]
	v_mfma_f32_16x16x32_bf16 v[116:119], v[158:161], v[210:213], v[116:119]
	v_mfma_f32_16x16x32_bf16 v[108:111], v[150:153], v[218:221], v[108:111]
	v_mfma_f32_16x16x32_bf16 v[100:103], v[158:161], v[218:221], v[100:103]
	v_mfma_f32_16x16x32_bf16 v[92:95], v[150:153], v[226:229], v[92:95]
	v_mfma_f32_16x16x32_bf16 v[84:87], v[158:161], v[226:229], v[84:87]
	v_mfma_f32_16x16x32_bf16 v[76:79], v[150:153], v[234:237], v[76:79]
	v_mfma_f32_16x16x32_bf16 v[68:71], v[158:161], v[234:237], v[68:71]
	s_setprio 0
	s_setprio 1
	v_mfma_f32_16x16x32_bf16 v[120:123], v[174:177], v[190:193], 0
	v_mfma_f32_16x16x32_bf16 v[112:115], v[182:185], v[190:193], 0
	v_mfma_f32_16x16x32_bf16 v[104:107], v[174:177], v[214:217], 0
	v_mfma_f32_16x16x32_bf16 v[96:99], v[182:185], v[214:217], 0
	v_mfma_f32_16x16x32_bf16 v[88:91], v[174:177], v[222:225], 0
	v_mfma_f32_16x16x32_bf16 v[80:83], v[182:185], v[222:225], 0
	v_mfma_f32_16x16x32_bf16 v[72:75], v[174:177], v[230:233], 0
	v_mfma_f32_16x16x32_bf16 v[64:67], v[182:185], v[230:233], 0
	v_mfma_f32_16x16x32_bf16 v[120:123], v[178:181], v[210:213], v[120:123]
	v_mfma_f32_16x16x32_bf16 v[112:115], v[186:189], v[210:213], v[112:115]
	v_mfma_f32_16x16x32_bf16 v[104:107], v[178:181], v[218:221], v[104:107]
	v_mfma_f32_16x16x32_bf16 v[96:99], v[186:189], v[218:221], v[96:99]
	v_mfma_f32_16x16x32_bf16 v[88:91], v[178:181], v[226:229], v[88:91]
	v_mfma_f32_16x16x32_bf16 v[80:83], v[186:189], v[226:229], v[80:83]
	v_mfma_f32_16x16x32_bf16 v[72:75], v[178:181], v[234:237], v[72:75]
	v_mfma_f32_16x16x32_bf16 v[64:67], v[186:189], v[234:237], v[64:67]
	s_setprio 0
	s_barrier
	s_add_i32 s51, s51, s34
	v_lshl_add_u64 v[194:195], s[2:3], 0, v[128:129]
	s_mov_b32 m0, s51
	ds_read_b128 v[190:193], v148 offset:16384
	ds_read_b128 v[210:213], v148 offset:17408
	ds_read_b128 v[214:217], v148 offset:18432
	ds_read_b128 v[218:221], v148 offset:19456
	ds_read_b128 v[222:225], v148 offset:20480
	ds_read_b128 v[226:229], v148 offset:21504
	ds_read_b128 v[230:233], v148 offset:22528
	ds_read_b128 v[234:237], v148 offset:23552
	global_load_lds_dwordx4 v[194:195], off
	s_add_i32 m0, s51, 0x2000
	s_add_u32 s52, s2, 0x40000
	v_lshl_add_u64 v[238:239], s[2:3], 0, v[130:131]
	s_addc_u32 s53, s3, 0
	s_add_i32 s51, s54, s34
	global_load_lds_dwordx4 v[238:239], off
	v_lshl_add_u64 v[240:241], s[52:53], 0, v[128:129]
	s_mov_b32 m0, s51
	v_lshl_add_u64 v[242:243], s[26:27], 0, v[132:133]
	global_load_lds_dwordx4 v[240:241], off
	v_lshl_add_u64 v[240:241], s[52:53], 0, v[130:131]
	s_add_i32 m0, s51, 0x2000
	s_nop 0
	global_load_lds_dwordx4 v[240:241], off
	v_lshl_add_u64 v[240:241], s[26:27], 0, v[134:135]
	s_mov_b32 m0, s35
	s_nop 0
	global_load_lds_dwordx4 v[240:241], off
	s_mov_b32 m0, s36
	s_nop 0
	global_load_lds_dwordx4 v[242:243], off
	s_waitcnt vmcnt(8)
	s_waitcnt lgkmcnt(0)
	s_barrier
	s_setprio 1
	s_waitcnt lgkmcnt(0)
	v_mfma_f32_16x16x32_bf16 v[60:63], v[140:143], v[190:193], 0
	v_mfma_f32_16x16x32_bf16 v[52:55], v[154:157], v[190:193], 0
	v_mfma_f32_16x16x32_bf16 v[44:47], v[140:143], v[214:217], 0
	v_mfma_f32_16x16x32_bf16 v[36:39], v[154:157], v[214:217], 0
	v_mfma_f32_16x16x32_bf16 v[28:31], v[140:143], v[222:225], 0
	v_mfma_f32_16x16x32_bf16 v[20:23], v[154:157], v[222:225], 0
	v_mfma_f32_16x16x32_bf16 v[12:15], v[140:143], v[230:233], 0
	v_mfma_f32_16x16x32_bf16 v[4:7], v[154:157], v[230:233], 0
	v_mfma_f32_16x16x32_bf16 v[60:63], v[150:153], v[210:213], v[60:63]
	v_mfma_f32_16x16x32_bf16 v[52:55], v[158:161], v[210:213], v[52:55]
	v_mfma_f32_16x16x32_bf16 v[44:47], v[150:153], v[218:221], v[44:47]
	v_mfma_f32_16x16x32_bf16 v[36:39], v[158:161], v[218:221], v[36:39]
	v_mfma_f32_16x16x32_bf16 v[28:31], v[150:153], v[226:229], v[28:31]
	v_mfma_f32_16x16x32_bf16 v[20:23], v[158:161], v[226:229], v[20:23]
	v_mfma_f32_16x16x32_bf16 v[12:15], v[150:153], v[234:237], v[12:15]
	v_mfma_f32_16x16x32_bf16 v[4:7], v[158:161], v[234:237], v[4:7]
	s_setprio 0
	s_setprio 1
	v_mfma_f32_16x16x32_bf16 v[56:59], v[174:177], v[190:193], 0
	v_mfma_f32_16x16x32_bf16 v[48:51], v[182:185], v[190:193], 0
	v_mfma_f32_16x16x32_bf16 v[40:43], v[174:177], v[214:217], 0
	v_mfma_f32_16x16x32_bf16 v[32:35], v[182:185], v[214:217], 0
	v_mfma_f32_16x16x32_bf16 v[24:27], v[174:177], v[222:225], 0
	v_mfma_f32_16x16x32_bf16 v[16:19], v[182:185], v[222:225], 0
	v_mfma_f32_16x16x32_bf16 v[8:11], v[174:177], v[230:233], 0
	v_mfma_f32_16x16x32_bf16 v[0:3], v[182:185], v[230:233], 0
	v_mfma_f32_16x16x32_bf16 v[56:59], v[178:181], v[210:213], v[56:59]
	v_mfma_f32_16x16x32_bf16 v[48:51], v[186:189], v[210:213], v[48:51]
	v_mfma_f32_16x16x32_bf16 v[40:43], v[178:181], v[218:221], v[40:43]
	v_mfma_f32_16x16x32_bf16 v[32:35], v[186:189], v[218:221], v[32:35]
	v_mfma_f32_16x16x32_bf16 v[24:27], v[178:181], v[226:229], v[24:27]
	v_mfma_f32_16x16x32_bf16 v[16:19], v[186:189], v[226:229], v[16:19]
	v_mfma_f32_16x16x32_bf16 v[8:11], v[178:181], v[234:237], v[8:11]
	v_mfma_f32_16x16x32_bf16 v[0:3], v[186:189], v[234:237], v[0:3]
	s_setprio 0
	s_barrier
	s_branch .Lpeel1_seg3
	.p2align	6
